# weight prep in GEMM tails rebalanced: bias-item workgroups skip the conversion items, which go to the other workgroups only
# speedup vs baseline: 1.0220x; 1.0074x over previous
; #define LAS __attribute__((address_space(3)))
; #define otid() ((wv << 6) | olane())
; __device__ __forceinline__ void convert_weights(LAS unsigned char* lds, KP p, int l, int wv) {
;     unsigned char* ws = p->ws;
;     const int tid_ = otid(); const int lane = tid_ & 63, wid = tid_ >> 6;
;     LAS float* scr = (LAS float*)(lds + wid * 8704);
;     const int gw = blockIdx.x * 8 + wid, NGW = gridDim.x * 8;
;     constexpr int I_IN = 16 * (DIN / 32), I_UQ = 6 * 24, I_UKV = 4 * 32, I_BR = 8 * 32, I_O = 16 * 32, I_F1 = 16 * 128, I_F2 = 64 * 32;
;     constexpr int NIT = I_IN + I_UQ + I_UKV + 3 * I_BR + I_O + I_F1 + I_F2;
;     const int BIG = 1 << 30;
;     for (int it = gw; it < NIT; it += NGW) {
;         int r = it;
;         if (r < I_IN) { tr_item(p->w_in + (size_t)l * DM * DIN, DIN, (bf16_t*)(ws + WS_WIN), DM, 0, NGATE0, NPM - NGATE0, 1, 0, scr, r, lane); continue; } r -= I_IN;
;         if (r < I_UQ) { const int nb = r % 24, hh = nb / 3, part = nb % 3, dest = part < 2 ? (2 * hh + part) * 32 : 512 + 32 * hh;
;             tr_item(p->w_uq + (size_t)l * 384 * 768, 768, (bf16_t*)(ws + WS_WUQ), 384, dest - 32 * nb, BIG, 0, 1, 0, scr, r, lane); continue; } r -= I_UQ;
;         if (r < I_UKV) { tr_item(p->w_ukv + (size_t)l * 256 * 1024, 1024, (bf16_t*)(ws + WS_WUKV), 256, 0, BIG, 0, 1, 0, scr, r, lane); continue; } r -= I_UKV;
;         if (r < 3 * I_BR) { const int z3 = r / I_BR, z = z3 == 2 ? 3 : z3; tr_item(p->w_branch + ((size_t)l * 4 + z) * 512 * 1024, 1024, (bf16_t*)(ws + WS_WBR), 512, z * 1024, BIG, 0, 1, 0, scr, r % I_BR, lane); continue; } r -= 3 * I_BR;
;         if (r < I_O) { tr_item(p->w_o + (size_t)l * DM * DM, DM, (bf16_t*)(ws + WS_WO4), 4096, 0, BIG, 0, 1, 0, scr, r, lane); continue; } r -= I_O;
;         if (r < I_F1) { tr_item(p->w_ff1 + (size_t)l * DM * DFF, DFF, (bf16_t*)(ws + WS_WF1), DM, 0, BIG, 0, 1, 0, scr, r, lane); continue; } r -= I_F1;
;         tr_item(p->w_ff2 + (size_t)l * DFF * DM, DM, (bf16_t*)(ws + WS_WF2), DFF, 0, BIG, 0, 1, 0, scr, r, lane);
;     }
;     { const int gt = blockIdx.x * 512 + otid(), NT = gridDim.x * 512; u32x4* z = (u32x4*)((bf16_t*)(ws + WS_WIN) + (size_t)NGATE0 * DM);
;       unsigned z0 = 0u; asm volatile("" : "+v"(z0));
;       for (int i = gt; i < (NPM - NGATE0) * DM / 8; i += NT) z[i] = (u32x4){z0, z0, z0, z0}; }
.LBB0_317:
	s_cmp_lt_u32 s79, 0x48
	s_cbranch_scc1 .Lp0b_skip
	v_readlane_b32 s0, v255, 6
	v_readlane_b32 s1, v255, 7
	v_readlane_b32 s2, v255, 23
	v_readlane_b32 s3, v255, 24
	v_readlane_b32 s4, v255, 25
	v_readlane_b32 s5, v255, 26
	v_readlane_b32 s6, v255, 29
	v_readlane_b32 s7, v255, 30
	s_nop 3
	v_writelane_b32 v255, s60, 49
	v_writelane_b32 v255, s66, 50
	v_writelane_b32 v255, s0, 51
	v_writelane_b32 v255, s1, 52
	v_writelane_b32 v255, s2, 53
	v_writelane_b32 v255, s3, 54
	v_writelane_b32 v255, s4, 55
	v_writelane_b32 v255, s5, 56
	v_writelane_b32 v255, s6, 57
	v_writelane_b32 v255, s7, 58
	s_sub_i32 s79, s79, 0x48
	s_movk_i32 s60, 0xb8
	s_mov_b32 s66, 0x17000
	s_movk_i32 s89, 0x47ff
	s_lshl_b32 s0, s79, 3
	s_lshl_b32 s1, s79, 9
	s_mov_b32 s2, 0x170000
	s_mov_b32 s3, 0
	s_mov_b32 s4, 0x5c0000
	s_movk_i32 s6, 0x3c0
	s_sub_i32 s5, s79, 64
	s_lshl_b32 s5, s5, 3
	s_cmp_lt_u32 s79, 64
	s_cselect_b32 s0, 0x2660, s5
	v_writelane_b32 v255, s0, 6
	v_writelane_b32 v255, s1, 7
	v_writelane_b32 v255, s2, 23
	v_writelane_b32 v255, s3, 24
	v_writelane_b32 v255, s4, 25
	v_writelane_b32 v255, s3, 26
	v_writelane_b32 v255, s6, 29
	v_writelane_b32 v255, s3, 30

; #define LAS __attribute__((address_space(3)))
; #define otid() ((wv << 6) | olane())
; __device__ __forceinline__ void convert_weights(LAS unsigned char* lds, KP p, int l, int wv) {
;     unsigned char* ws = p->ws;
;     const int tid_ = otid(); const int lane = tid_ & 63, wid = tid_ >> 6;
;     LAS float* scr = (LAS float*)(lds + wid * 8704);
;     const int gw = blockIdx.x * 8 + wid, NGW = gridDim.x * 8;
;     constexpr int I_IN = 16 * (DIN / 32), I_UQ = 6 * 24, I_UKV = 4 * 32, I_BR = 8 * 32, I_O = 16 * 32, I_F1 = 16 * 128, I_F2 = 64 * 32;
;     constexpr int NIT = I_IN + I_UQ + I_UKV + 3 * I_BR + I_O + I_F1 + I_F2;
;     const int BIG = 1 << 30;
;     for (int it = gw; it < NIT; it += NGW) {
;         int r = it;
;         if (r < I_IN) { tr_item(p->w_in + (size_t)l * DM * DIN, DIN, (bf16_t*)(ws + WS_WIN), DM, 0, NGATE0, NPM - NGATE0, 1, 0, scr, r, lane); continue; } r -= I_IN;
;         if (r < I_UQ) { const int nb = r % 24, hh = nb / 3, part = nb % 3, dest = part < 2 ? (2 * hh + part) * 32 : 512 + 32 * hh;
;             tr_item(p->w_uq + (size_t)l * 384 * 768, 768, (bf16_t*)(ws + WS_WUQ), 384, dest - 32 * nb, BIG, 0, 1, 0, scr, r, lane); continue; } r -= I_UQ;
;         if (r < I_UKV) { tr_item(p->w_ukv + (size_t)l * 256 * 1024, 1024, (bf16_t*)(ws + WS_WUKV), 256, 0, BIG, 0, 1, 0, scr, r, lane); continue; } r -= I_UKV;
;         if (r < 3 * I_BR) { const int z3 = r / I_BR, z = z3 == 2 ? 3 : z3; tr_item(p->w_branch + ((size_t)l * 4 + z) * 512 * 1024, 1024, (bf16_t*)(ws + WS_WBR), 512, z * 1024, BIG, 0, 1, 0, scr, r % I_BR, lane); continue; } r -= 3 * I_BR;
;         if (r < I_O) { tr_item(p->w_o + (size_t)l * DM * DM, DM, (bf16_t*)(ws + WS_WO4), 4096, 0, BIG, 0, 1, 0, scr, r, lane); continue; } r -= I_O;
;         if (r < I_F1) { tr_item(p->w_ff1 + (size_t)l * DM * DFF, DFF, (bf16_t*)(ws + WS_WF1), DM, 0, BIG, 0, 1, 0, scr, r, lane); continue; } r -= I_F1;
;         tr_item(p->w_ff2 + (size_t)l * DFF * DM, DM, (bf16_t*)(ws + WS_WF2), DFF, 0, BIG, 0, 1, 0, scr, r, lane);
;     }
;     { const int gt = blockIdx.x * 512 + otid(), NT = gridDim.x * 512; u32x4* z = (u32x4*)((bf16_t*)(ws + WS_WIN) + (size_t)NGATE0 * DM);
;       unsigned z0 = 0u; asm volatile("" : "+v"(z0));
;       for (int i = gt; i < (NPM - NGATE0) * DM / 8; i += NT) z[i] = (u32x4){z0, z0, z0, z0}; }
.LBB0_1209:
	s_cmp_eq_u32 s90, 3
	s_cbranch_scc1 .Lp0a_skip
	s_cmp_lt_u32 s79, 32
	s_cbranch_scc1 .Lp0a_skip
	v_readlane_b32 s0, v255, 6
	v_readlane_b32 s1, v255, 7
	v_readlane_b32 s2, v255, 23
	v_readlane_b32 s3, v255, 24
	v_readlane_b32 s4, v255, 25
	v_readlane_b32 s5, v255, 26
	v_readlane_b32 s6, v255, 29
	v_readlane_b32 s7, v255, 30
	s_nop 3
	v_writelane_b32 v255, s34, 47
	v_writelane_b32 v255, s35, 48
	v_writelane_b32 v255, s60, 49
	v_writelane_b32 v255, s66, 50
	v_writelane_b32 v255, s0, 51
	v_writelane_b32 v255, s1, 52
	v_writelane_b32 v255, s2, 53
	v_writelane_b32 v255, s3, 54
	v_writelane_b32 v255, s4, 55
	v_writelane_b32 v255, s5, 56
	v_writelane_b32 v255, s6, 57
	v_writelane_b32 v255, s7, 58
	s_sub_i32 s79, s79, 32
	s_movk_i32 s60, 0xe0
	s_mov_b32 s66, 0x1c000
	s_add_i32 s90, s90, 1
	s_lshl_b32 s0, s79, 3
	s_lshl_b32 s1, s79, 9
	s_mov_b32 s2, 0x1c0000
	s_mov_b32 s3, 0
	s_mov_b32 s4, 0x700000
	s_movk_i32 s6, 0x2e8
	s_sub_i32 s5, s79, 0x83
	s_lshl_b32 s5, s5, 3
	s_cmp_lt_u32 s79, 0x83
	s_cselect_b32 s0, 0x1460, s5
	s_mov_b32 s7, 1
	v_writelane_b32 v255, s0, 6
	v_writelane_b32 v255, s1, 7
	v_writelane_b32 v255, s2, 23
	v_writelane_b32 v255, s3, 24
	v_writelane_b32 v255, s4, 25
	v_writelane_b32 v255, s3, 26
	v_writelane_b32 v255, s6, 29
	v_writelane_b32 v255, s3, 30
